# v028
# speedup vs baseline: 1.0132x; 1.0132x over previous
.LBB0_310:
	s_add_i32 s40, s19, 0
	v_add_u32_e32 v210, s40, v182
	ds_read_b128 v[2:5], v210
	ds_read_b128 v[6:9], v210 offset:8192
	v_add_u32_e32 v208, s40, v183
	ds_read_b128 v[10:13], v208
	v_add_u32_e32 v209, s40, v184
	ds_read_b128 v[80:83], v209
	s_lshl_b32 s80, s18, 7
	v_add_u32_e32 v211, s40, v185
	v_add_u32_e32 v0, s80, v198
	s_waitcnt lgkmcnt(0)
	v_mfma_f32_32x32x16_bf16 v[112:127], v[2:5], v[144:147], 0
	ds_read_b128 v[2:5], v208 offset:8192
	s_or_b32 s16, s80, 63
	v_cvt_f32_i32_e32 v0, v0
	s_cmp_ge_i32 s16, s23
	s_cselect_b64 s[16:17], -1, 0
	s_cmp_le_i32 s80, s47
	s_cselect_b64 s[18:19], -1, 0
	v_mfma_f32_32x32x16_bf16 v[112:127], v[10:13], v[148:151], v[112:127]
	ds_read_b128 v[10:13], v209 offset:8192
	ds_read_b128 v[84:87], v211
	ds_read_b128 v[88:91], v211 offset:8192
	v_mfma_f32_32x32x16_bf16 v[112:127], v[80:83], v[152:155], v[112:127]
	v_mfma_f32_32x32x16_bf16 v[128:143], v[6:9], v[144:147], 0
	v_add_u32_e32 v14, s40, v187
	v_add_u32_e32 v204, s40, v191
	v_add_u32_e32 v15, s40, v188
	v_add_u32_e32 v202, s40, v189
	v_add_u32_e32 v203, s40, v190
	ds_read_b64_tr_b16 v[160:161], v14 offset:16384
	ds_read_b64_tr_b16 v[162:163], v15 offset:16384
	ds_read_b64_tr_b16 v[6:7], v202 offset:16384
	ds_read_b64_tr_b16 v[8:9], v203 offset:16384
	v_add_u32_e32 v205, s40, v192
	s_waitcnt lgkmcnt(7)
	v_mfma_f32_32x32x16_bf16 v[128:143], v[2:5], v[148:151], v[128:143]
	v_add_u32_e32 v206, s40, v193
	v_add_u32_e32 v207, s40, v196
	s_waitcnt lgkmcnt(6)
	v_mfma_f32_32x32x16_bf16 v[128:143], v[10:13], v[152:155], v[128:143]
	ds_read_b64_tr_b16 v[10:11], v204 offset:16384
	ds_read_b64_tr_b16 v[12:13], v205 offset:16384
	ds_read_b64_tr_b16 v[2:3], v206 offset:16384
	ds_read_b64_tr_b16 v[4:5], v207 offset:16384
	s_waitcnt lgkmcnt(8)
	v_mfma_f32_32x32x16_bf16 v[128:143], v[88:91], v[156:159], v[128:143]
	v_mfma_f32_32x32x16_bf16 v[112:127], v[84:87], v[156:159], v[112:127]
	s_and_b64 s[18:19], s[16:17], s[18:19]
	s_andn2_b64 vcc, exec, s[18:19]
	s_mov_b64 s[18:19], -1
	s_cbranch_vccz .LBB0_312
	v_cndmask_b32_e64 v94, v176, -v176, s[16:17]
	v_fma_f32 v212, v94, v0, -v180
	v_add_f32_e32 v213, v197, v212
	v_fmamk_f32 v82, v94, 0x427c0000, v213
	v_max_f32_e32 v82, v82, v213
	s_andn2_b64 s[54:55], exec, s[14:15]
	v_cmp_lt_f32_e32 vcc, s70, v82
	s_or_b64 vcc, vcc, s[54:55]
	s_cbranch_vccnz .Lmy_slow0
	v_fma_f32 v80, 0, v94, v212
	v_add_f32_e32 v81, v94, v212
	v_fma_f32 v96, v112, s62, v80
	v_fma_f32 v97, v113, s62, v81
	v_fma_f32 v80, v94, s76, v212
	v_fma_f32 v81, v94, s77, v212
	v_fma_f32 v98, v114, s62, v80
	v_fma_f32 v99, v115, s62, v81
	v_fma_f32 v80, v94, s70, v212
	v_fma_f32 v81, v94, s71, v212
	v_fma_f32 v100, v116, s62, v80
	v_fma_f32 v101, v117, s62, v81
	v_fma_f32 v80, v94, s74, v212
	v_fma_f32 v81, v94, s75, v212
	v_fma_f32 v102, v118, s62, v80
	v_fma_f32 v103, v119, s62, v81
	v_fma_f32 v80, v94, s28, v212
	v_fma_f32 v81, v94, s29, v212
	v_fma_f32 v104, v120, s62, v80
	v_fma_f32 v105, v121, s62, v81
	v_fma_f32 v80, v94, s26, v212
	v_fma_f32 v81, v94, s27, v212
	v_fma_f32 v106, v122, s62, v80
	v_fma_f32 v107, v123, s62, v81
	v_fma_f32 v80, v94, s86, v212
	v_fma_f32 v81, v94, s87, v212
	v_fma_f32 v108, v124, s62, v80
	v_fma_f32 v109, v125, s62, v81
	v_fma_f32 v80, v94, s72, v212
	v_fma_f32 v81, v94, s73, v212
	v_fma_f32 v110, v126, s62, v80
	v_fma_f32 v111, v127, s62, v81
	v_fma_f32 v80, v94, s68, v212
	v_fma_f32 v81, v94, s69, v212
	v_fma_f32 v80, v128, s62, v80
	v_fma_f32 v81, v129, s62, v81
	v_fma_f32 v82, v94, s60, v212
	v_fma_f32 v83, v94, s61, v212
	v_fma_f32 v82, v130, s62, v82
	v_fma_f32 v83, v131, s62, v83
	v_fma_f32 v84, v94, s34, v212
	v_fma_f32 v85, v94, s35, v212
	v_fma_f32 v84, v132, s62, v84
	v_fma_f32 v85, v133, s62, v85
	v_fma_f32 v86, v94, s88, v212
	v_fma_f32 v87, v94, s89, v212
	v_fma_f32 v86, v134, s62, v86
	v_fma_f32 v87, v135, s62, v87
	v_fma_f32 v88, v94, s90, v212
	v_fma_f32 v89, v94, s91, v212
	v_fma_f32 v88, v136, s62, v88
	v_fma_f32 v89, v137, s62, v89
	v_fma_f32 v90, v94, s92, v212
	v_fma_f32 v91, v94, s93, v212
	v_fma_f32 v90, v138, s62, v90
	v_fma_f32 v91, v139, s62, v91
	v_fma_f32 v92, v94, s94, v212
	v_fma_f32 v93, v94, s95, v212
	v_fma_f32 v92, v140, s62, v92
	v_fma_f32 v93, v141, s62, v93
	v_fma_f32 v95, v94, s97, v212
	v_fma_f32 v94, v94, s96, v212
	v_fma_f32 v94, v142, s62, v94
	v_fma_f32 v95, v143, s62, v95
	s_branch .LBB0_321
.Lmy_slow0:
	v_fma_f32 v80, 0, v94, v212
	v_add_f32_e32 v81, v94, v212
	s_nop 3
	v_fma_f32 v96, v112, s62, v80
	v_fma_f32 v97, v113, s62, v81
	v_fma_f32 v80, v94, s76, v212
	v_fma_f32 v81, v94, s77, v212
	v_max3_f32 v82, v96, s36, v97
	v_fma_f32 v98, v114, s62, v80
	v_fma_f32 v99, v115, s62, v81
	v_fma_f32 v80, v94, s70, v212
	v_fma_f32 v81, v94, s71, v212
	v_max3_f32 v82, v82, v98, v99
	v_fma_f32 v100, v116, s62, v80
	v_fma_f32 v101, v117, s62, v81
	v_fma_f32 v80, v94, s74, v212
	v_fma_f32 v81, v94, s75, v212
	v_max3_f32 v82, v82, v100, v101
	v_fma_f32 v102, v118, s62, v80
	v_fma_f32 v103, v119, s62, v81
	v_fma_f32 v80, v94, s28, v212
	v_fma_f32 v81, v94, s29, v212
	v_max3_f32 v82, v82, v102, v103
	v_fma_f32 v104, v120, s62, v80
	v_fma_f32 v105, v121, s62, v81
	v_fma_f32 v80, v94, s26, v212
	v_fma_f32 v81, v94, s27, v212
	v_max3_f32 v82, v82, v104, v105
	v_fma_f32 v106, v122, s62, v80
	v_fma_f32 v107, v123, s62, v81
	v_fma_f32 v80, v94, s86, v212
	v_fma_f32 v81, v94, s87, v212
	v_max3_f32 v82, v82, v106, v107
	v_fma_f32 v108, v124, s62, v80
	v_fma_f32 v109, v125, s62, v81
	v_fma_f32 v80, v94, s72, v212
	v_fma_f32 v81, v94, s73, v212
	v_max3_f32 v82, v82, v108, v109
	v_fma_f32 v110, v126, s62, v80
	v_fma_f32 v111, v127, s62, v81
	s_nop 0
	v_max3_f32 v82, v82, v110, v111
	v_fma_f32 v80, v94, s68, v212
	v_fma_f32 v81, v94, s69, v212
	v_fma_f32 v80, v128, s62, v80
	v_fma_f32 v81, v129, s62, v81
	s_mov_b64 s[18:19], 0
	v_max3_f32 v84, v82, v80, v81
	v_fma_f32 v82, v94, s60, v212
	v_fma_f32 v83, v94, s61, v212
	v_fma_f32 v82, v130, s62, v82
	v_fma_f32 v83, v131, s62, v83
	s_nop 0
	v_max3_f32 v86, v84, v82, v83
	v_fma_f32 v84, v94, s34, v212
	v_fma_f32 v85, v94, s35, v212
	v_fma_f32 v84, v132, s62, v84
	v_fma_f32 v85, v133, s62, v85
	s_nop 0
	v_max3_f32 v88, v86, v84, v85
	v_fma_f32 v86, v94, s88, v212
	v_fma_f32 v87, v94, s89, v212
	v_fma_f32 v86, v134, s62, v86
	v_fma_f32 v87, v135, s62, v87
	s_nop 0
	v_max3_f32 v90, v88, v86, v87
	v_fma_f32 v88, v94, s90, v212
	v_fma_f32 v89, v94, s91, v212
	v_fma_f32 v88, v136, s62, v88
	v_fma_f32 v89, v137, s62, v89
	s_nop 0
	v_max3_f32 v92, v90, v88, v89
	v_fma_f32 v90, v94, s92, v212
	v_fma_f32 v91, v94, s93, v212
	v_fma_f32 v90, v138, s62, v90
	v_fma_f32 v91, v139, s62, v91
	s_nop 0
	v_max3_f32 v95, v92, v90, v91
	v_fma_f32 v92, v94, s94, v212
	v_fma_f32 v93, v94, s95, v212
	v_fma_f32 v92, v140, s62, v92
	v_fma_f32 v93, v141, s62, v93
	s_nop 0
	v_max3_f32 v213, v95, v92, v93
	v_fma_f32 v95, v94, s97, v212
	v_fma_f32 v94, v94, s96, v212
	v_fma_f32 v94, v142, s62, v94
	v_fma_f32 v95, v143, s62, v95
	s_nop 0
	v_max3_f32 v212, v213, v94, v95

.LBB0_321:
	v_exp_f32_e32 v212, v96
	v_exp_f32_e32 v213, v97
	v_exp_f32_e32 v214, v98
	v_exp_f32_e32 v215, v99
	v_exp_f32_e32 v216, v100
	v_exp_f32_e32 v217, v101
	v_exp_f32_e32 v218, v102
	v_exp_f32_e32 v219, v103
	v_cvt_pk_bf16_f32 v96, v212, v213
	v_cvt_pk_bf16_f32 v97, v214, v215
	v_cvt_pk_bf16_f32 v98, v216, v217
	v_cvt_pk_bf16_f32 v99, v218, v219
	s_waitcnt lgkmcnt(4)
	s_nop 0
	v_mfma_f32_32x32x16_bf16 v[48:63], v[6:9], v[96:99], v[48:63]
	s_waitcnt lgkmcnt(2)
	v_mfma_f32_32x32x16_bf16 v[32:47], v[10:13], v[96:99], v[32:47]
	ds_read_b64_tr_b16 v[6:7], v14 offset:20480
	ds_read_b64_tr_b16 v[8:9], v15 offset:20480
	ds_read_b64_tr_b16 v[10:11], v202 offset:20480
	ds_read_b64_tr_b16 v[12:13], v203 offset:20480
	ds_read_b64_tr_b16 v[100:101], v204 offset:20480
	ds_read_b64_tr_b16 v[102:103], v205 offset:20480
	ds_read_b64_tr_b16 v[112:113], v206 offset:20480
	ds_read_b64_tr_b16 v[114:115], v207 offset:20480
	v_mfma_f32_32x32x16_bf16 v[64:79], v[160:163], v[96:99], v[64:79]
	s_waitcnt lgkmcnt(8)
	v_mfma_f32_32x32x16_bf16 v[16:31], v[2:5], v[96:99], v[16:31]
	v_exp_f32_e32 v220, v104
	v_exp_f32_e32 v221, v105
	v_exp_f32_e32 v222, v106
	v_exp_f32_e32 v223, v107
	v_exp_f32_e32 v224, v108
	v_exp_f32_e32 v225, v109
	v_exp_f32_e32 v228, v110
	v_exp_f32_e32 v246, v111
	v_cvt_pk_bf16_f32 v2, v220, v221
	v_cvt_pk_bf16_f32 v3, v222, v223
	v_cvt_pk_bf16_f32 v4, v224, v225
	v_cvt_pk_bf16_f32 v5, v228, v246
	s_waitcnt lgkmcnt(6)
	s_nop 0
	v_mfma_f32_32x32x16_bf16 v[64:79], v[6:9], v[2:5], v[64:79]
	s_waitcnt lgkmcnt(4)
	v_mfma_f32_32x32x16_bf16 v[48:63], v[10:13], v[2:5], v[48:63]
	s_waitcnt lgkmcnt(2)
	v_mfma_f32_32x32x16_bf16 v[32:47], v[100:103], v[2:5], v[32:47]
	ds_read_b64_tr_b16 v[6:7], v14 offset:24576
	ds_read_b64_tr_b16 v[8:9], v15 offset:24576
	ds_read_b64_tr_b16 v[10:11], v202 offset:24576
	ds_read_b64_tr_b16 v[12:13], v203 offset:24576
	ds_read_b64_tr_b16 v[96:97], v204 offset:24576
	ds_read_b64_tr_b16 v[98:99], v205 offset:24576
	ds_read_b64_tr_b16 v[100:101], v206 offset:24576
	ds_read_b64_tr_b16 v[102:103], v207 offset:24576
	s_waitcnt lgkmcnt(8)
	v_mfma_f32_32x32x16_bf16 v[16:31], v[112:115], v[2:5], v[16:31]
	v_exp_f32_e32 v247, v80
	v_exp_f32_e32 v248, v81
	v_exp_f32_e32 v249, v82
	v_exp_f32_e32 v250, v83
	v_exp_f32_e32 v251, v84
	v_exp_f32_e32 v252, v85
	v_exp_f32_e32 v231, v86
	v_exp_f32_e32 v232, v87
	v_cvt_pk_bf16_f32 v2, v247, v248
	v_cvt_pk_bf16_f32 v3, v249, v250
	v_cvt_pk_bf16_f32 v4, v251, v252
	v_cvt_pk_bf16_f32 v5, v231, v232
	s_waitcnt lgkmcnt(6)
	s_nop 0
	v_mfma_f32_32x32x16_bf16 v[64:79], v[6:9], v[2:5], v[64:79]
	s_waitcnt lgkmcnt(4)
	v_mfma_f32_32x32x16_bf16 v[48:63], v[10:13], v[2:5], v[48:63]
	ds_read_b64_tr_b16 v[6:7], v14 offset:28672
	ds_read_b64_tr_b16 v[8:9], v15 offset:28672
	ds_read_b64_tr_b16 v[10:11], v202 offset:28672
	ds_read_b64_tr_b16 v[12:13], v203 offset:28672
	ds_read_b64_tr_b16 v[80:81], v204 offset:28672
	ds_read_b64_tr_b16 v[82:83], v205 offset:28672
	ds_read_b64_tr_b16 v[84:85], v206 offset:28672
	ds_read_b64_tr_b16 v[86:87], v207 offset:28672
	s_waitcnt lgkmcnt(10)
	v_mfma_f32_32x32x16_bf16 v[32:47], v[96:99], v[2:5], v[32:47]
	s_waitcnt lgkmcnt(8)
	v_mfma_f32_32x32x16_bf16 v[16:31], v[100:103], v[2:5], v[16:31]
	v_exp_f32_e32 v233, v88
	v_exp_f32_e32 v234, v89
	v_exp_f32_e32 v235, v90
	v_exp_f32_e32 v236, v91
	v_exp_f32_e32 v237, v92
	v_exp_f32_e32 v238, v93
	v_exp_f32_e32 v239, v94
	v_exp_f32_e32 v240, v95
	v_cvt_pk_bf16_f32 v2, v233, v234
	v_cvt_pk_bf16_f32 v3, v235, v236
	v_cvt_pk_bf16_f32 v4, v237, v238
	v_cvt_pk_bf16_f32 v5, v239, v240
	s_waitcnt lgkmcnt(6)
	s_nop 0
	v_mfma_f32_32x32x16_bf16 v[64:79], v[6:9], v[2:5], v[64:79]
	s_waitcnt lgkmcnt(4)
	v_mfma_f32_32x32x16_bf16 v[48:63], v[10:13], v[2:5], v[48:63]
	s_waitcnt lgkmcnt(2)
	v_mfma_f32_32x32x16_bf16 v[32:47], v[80:83], v[2:5], v[32:47]
	s_waitcnt lgkmcnt(0)
	v_mfma_f32_32x32x16_bf16 v[16:31], v[84:87], v[2:5], v[16:31]
	ds_read_b128 v[2:5], v210 offset:32768
	ds_read_b128 v[6:9], v210 offset:40960
	s_or_b32 s18, s80, 64
	v_add_u32_e32 v0, s18, v198
	s_or_b32 s14, s80, 0x7f
	s_waitcnt lgkmcnt(1)
	v_mfma_f32_32x32x16_bf16 v[112:127], v[2:5], v[144:147], 0
	ds_read_b128 v[2:5], v208 offset:32768
	ds_read_b128 v[10:13], v208 offset:40960
	ds_read_b128 v[80:83], v209 offset:32768
	v_cvt_f32_i32_e32 v0, v0
	s_cmp_ge_i32 s14, s23
	s_cselect_b64 s[14:15], -1, 0
	s_cmp_le_i32 s18, s47
	s_cselect_b64 s[16:17], -1, 0
	s_waitcnt lgkmcnt(2)
	v_mfma_f32_32x32x16_bf16 v[112:127], v[2:5], v[148:151], v[112:127]
	ds_read_b128 v[2:5], v209 offset:40960
	ds_read_b128 v[84:87], v211 offset:32768
	ds_read_b128 v[88:91], v211 offset:40960
	s_waitcnt lgkmcnt(3)
	v_mfma_f32_32x32x16_bf16 v[112:127], v[80:83], v[152:155], v[112:127]
	v_mfma_f32_32x32x16_bf16 v[128:143], v[6:9], v[144:147], 0
	v_mfma_f32_32x32x16_bf16 v[128:143], v[10:13], v[148:151], v[128:143]
	s_waitcnt lgkmcnt(2)
	v_mfma_f32_32x32x16_bf16 v[128:143], v[2:5], v[152:155], v[128:143]
	ds_read_b64_tr_b16 v[160:161], v14 offset:49152
	ds_read_b64_tr_b16 v[162:163], v15 offset:49152
	ds_read_b64_tr_b16 v[10:11], v202 offset:49152
	ds_read_b64_tr_b16 v[12:13], v203 offset:49152
	ds_read_b64_tr_b16 v[6:7], v204 offset:49152
	ds_read_b64_tr_b16 v[8:9], v205 offset:49152
	ds_read_b64_tr_b16 v[2:3], v206 offset:49152
	ds_read_b64_tr_b16 v[4:5], v207 offset:49152
	s_waitcnt lgkmcnt(8)
	v_mfma_f32_32x32x16_bf16 v[128:143], v[88:91], v[156:159], v[128:143]
	v_mfma_f32_32x32x16_bf16 v[112:127], v[84:87], v[156:159], v[112:127]
	s_and_b64 s[18:19], s[14:15], s[16:17]
	s_mov_b64 s[16:17], -1
	s_and_b64 vcc, exec, s[18:19]
	s_cbranch_vccnz .LBB0_323
	v_cndmask_b32_e64 v94, v176, -v176, s[14:15]
	v_fma_f32 v208, v94, v0, -v180
	v_add_f32_e32 v209, v197, v208
	v_fmamk_f32 v82, v94, 0x427c0000, v209
	v_max_f32_e32 v82, v82, v209
	v_cmp_lt_f32_e32 vcc, s70, v82
	s_cbranch_vccnz .Lmy_slow1
	v_fma_f32 v80, 0, v94, v208
	v_add_f32_e32 v81, v94, v208
	v_fma_f32 v96, v112, s62, v80
	v_fma_f32 v97, v113, s62, v81
	v_fma_f32 v80, v94, s76, v208
	v_fma_f32 v81, v94, s77, v208
	v_fma_f32 v98, v114, s62, v80
	v_fma_f32 v99, v115, s62, v81
	v_fma_f32 v80, v94, s70, v208
	v_fma_f32 v81, v94, s71, v208
	v_fma_f32 v100, v116, s62, v80
	v_fma_f32 v101, v117, s62, v81
	v_fma_f32 v80, v94, s74, v208
	v_fma_f32 v81, v94, s75, v208
	v_fma_f32 v102, v118, s62, v80
	v_fma_f32 v103, v119, s62, v81
	v_fma_f32 v80, v94, s28, v208
	v_fma_f32 v81, v94, s29, v208
	v_fma_f32 v104, v120, s62, v80
	v_fma_f32 v105, v121, s62, v81
	v_fma_f32 v80, v94, s26, v208
	v_fma_f32 v81, v94, s27, v208
	v_fma_f32 v106, v122, s62, v80
	v_fma_f32 v107, v123, s62, v81
	v_fma_f32 v80, v94, s86, v208
	v_fma_f32 v81, v94, s87, v208
	v_fma_f32 v108, v124, s62, v80
	v_fma_f32 v109, v125, s62, v81
	v_fma_f32 v80, v94, s72, v208
	v_fma_f32 v81, v94, s73, v208
	v_fma_f32 v110, v126, s62, v80
	v_fma_f32 v111, v127, s62, v81
	v_fma_f32 v80, v94, s68, v208
	v_fma_f32 v81, v94, s69, v208
	v_fma_f32 v80, v128, s62, v80
	v_fma_f32 v81, v129, s62, v81
	v_fma_f32 v82, v94, s60, v208
	v_fma_f32 v83, v94, s61, v208
	v_fma_f32 v82, v130, s62, v82
	v_fma_f32 v83, v131, s62, v83
	v_fma_f32 v84, v94, s34, v208
	v_fma_f32 v85, v94, s35, v208
	v_fma_f32 v84, v132, s62, v84
	v_fma_f32 v85, v133, s62, v85
	v_fma_f32 v86, v94, s88, v208
	v_fma_f32 v87, v94, s89, v208
	v_fma_f32 v86, v134, s62, v86
	v_fma_f32 v87, v135, s62, v87
	v_fma_f32 v88, v94, s90, v208
	v_fma_f32 v89, v94, s91, v208
	v_fma_f32 v88, v136, s62, v88
	v_fma_f32 v89, v137, s62, v89
	v_fma_f32 v90, v94, s92, v208
	v_fma_f32 v91, v94, s93, v208
	v_fma_f32 v90, v138, s62, v90
	v_fma_f32 v91, v139, s62, v91
	v_fma_f32 v92, v94, s94, v208
	v_fma_f32 v93, v94, s95, v208
	v_fma_f32 v92, v140, s62, v92
	v_fma_f32 v93, v141, s62, v93
	v_fma_f32 v95, v94, s97, v208
	v_fma_f32 v94, v94, s96, v208
	v_fma_f32 v94, v142, s62, v94
	v_fma_f32 v95, v143, s62, v95
	s_branch .Lmy_fast1_sum
.Lmy_slow1:
	v_fma_f32 v80, 0, v94, v208
	v_add_f32_e32 v81, v94, v208
	s_nop 3
	v_fma_f32 v96, v112, s62, v80
	v_fma_f32 v97, v113, s62, v81
	v_fma_f32 v80, v94, s76, v208
	v_fma_f32 v81, v94, s77, v208
	v_max3_f32 v82, v96, s36, v97
	v_fma_f32 v98, v114, s62, v80
	v_fma_f32 v99, v115, s62, v81
	v_fma_f32 v80, v94, s70, v208
	v_fma_f32 v81, v94, s71, v208
	v_max3_f32 v82, v82, v98, v99
	v_fma_f32 v100, v116, s62, v80
	v_fma_f32 v101, v117, s62, v81
	v_fma_f32 v80, v94, s74, v208
	v_fma_f32 v81, v94, s75, v208
	v_max3_f32 v82, v82, v100, v101
	v_fma_f32 v102, v118, s62, v80
	v_fma_f32 v103, v119, s62, v81
	v_fma_f32 v80, v94, s28, v208
	v_fma_f32 v81, v94, s29, v208
	v_max3_f32 v82, v82, v102, v103
	v_fma_f32 v104, v120, s62, v80
	v_fma_f32 v105, v121, s62, v81
	v_fma_f32 v80, v94, s26, v208
	v_fma_f32 v81, v94, s27, v208
	v_max3_f32 v82, v82, v104, v105
	v_fma_f32 v106, v122, s62, v80
	v_fma_f32 v107, v123, s62, v81
	v_fma_f32 v80, v94, s86, v208
	v_fma_f32 v81, v94, s87, v208
	v_max3_f32 v82, v82, v106, v107
	v_fma_f32 v108, v124, s62, v80
	v_fma_f32 v109, v125, s62, v81
	v_fma_f32 v80, v94, s72, v208
	v_fma_f32 v81, v94, s73, v208
	v_max3_f32 v82, v82, v108, v109
	v_fma_f32 v110, v126, s62, v80
	v_fma_f32 v111, v127, s62, v81
	s_nop 0
	v_max3_f32 v82, v82, v110, v111
	v_fma_f32 v80, v94, s68, v208
	v_fma_f32 v81, v94, s69, v208
	v_fma_f32 v80, v128, s62, v80
	v_fma_f32 v81, v129, s62, v81
	s_mov_b64 s[16:17], 0
	v_max3_f32 v84, v82, v80, v81
	v_fma_f32 v82, v94, s60, v208
	v_fma_f32 v83, v94, s61, v208
	v_fma_f32 v82, v130, s62, v82
	v_fma_f32 v83, v131, s62, v83
	s_nop 0
	v_max3_f32 v86, v84, v82, v83
	v_fma_f32 v84, v94, s34, v208
	v_fma_f32 v85, v94, s35, v208
	v_fma_f32 v84, v132, s62, v84
	v_fma_f32 v85, v133, s62, v85
	s_nop 0
	v_max3_f32 v88, v86, v84, v85
	v_fma_f32 v86, v94, s88, v208
	v_fma_f32 v87, v94, s89, v208
	v_fma_f32 v86, v134, s62, v86
	v_fma_f32 v87, v135, s62, v87
	s_nop 0
	v_max3_f32 v90, v88, v86, v87
	v_fma_f32 v88, v94, s90, v208
	v_fma_f32 v89, v94, s91, v208
	v_fma_f32 v88, v136, s62, v88
	v_fma_f32 v89, v137, s62, v89
	s_nop 0
	v_max3_f32 v92, v90, v88, v89
	v_fma_f32 v90, v94, s92, v208
	v_fma_f32 v91, v94, s93, v208
	v_fma_f32 v90, v138, s62, v90
	v_fma_f32 v91, v139, s62, v91
	s_nop 0
	v_max3_f32 v95, v92, v90, v91
	v_fma_f32 v92, v94, s94, v208
	v_fma_f32 v93, v94, s95, v208
	v_fma_f32 v92, v140, s62, v92
	v_fma_f32 v93, v141, s62, v93
	s_nop 0
	v_max3_f32 v209, v95, v92, v93
	v_fma_f32 v95, v94, s97, v208
	v_fma_f32 v94, v94, s96, v208
	v_fma_f32 v94, v142, s62, v94
	v_fma_f32 v95, v143, s62, v95
	s_nop 0
	v_max3_f32 v208, v209, v94, v95

.Lmy_fast1_sum:
	v_add_f32_e32 v0, 0, v212
	v_add_f32_e32 v0, v213, v0
	v_add_f32_e32 v0, v214, v0
	v_add_f32_e32 v0, v215, v0
	v_add_f32_e32 v0, v216, v0
	v_add_f32_e32 v0, v217, v0
	v_add_f32_e32 v0, v218, v0
	v_add_f32_e32 v0, v219, v0
	v_add_f32_e32 v0, v220, v0
	v_add_f32_e32 v0, v221, v0
	v_add_f32_e32 v0, v222, v0
	v_add_f32_e32 v0, v223, v0
	v_add_f32_e32 v0, v224, v0
	v_add_f32_e32 v0, v225, v0
	v_add_f32_e32 v0, v228, v0
	v_add_f32_e32 v0, v246, v0
	v_add_f32_e32 v0, v247, v0
	v_add_f32_e32 v0, v248, v0
	v_add_f32_e32 v0, v249, v0
	v_add_f32_e32 v0, v250, v0
	v_add_f32_e32 v0, v251, v0
	v_add_f32_e32 v0, v252, v0
	v_add_f32_e32 v0, v231, v0
	v_add_f32_e32 v0, v232, v0
	v_add_f32_e32 v0, v233, v0
	v_add_f32_e32 v0, v234, v0
	v_add_f32_e32 v0, v235, v0
	v_add_f32_e32 v0, v236, v0
	v_add_f32_e32 v0, v237, v0
	v_add_f32_e32 v0, v238, v0
	v_add_f32_e32 v0, v239, v0
	v_add_f32_e32 v0, v240, v0
	v_add_f32_e32 v0, v201, v0
	s_branch .LBB0_327
